# phase-2 QM rotary epilogue also loads cos/sin one step ahead into spare VGPRs (counted vmcnt(2)); phase-1 lookahead kept
# speedup vs baseline: 1.0395x; 1.0016x over previous
.LBB0_394:
	s_andn2_b64 vcc, exec, s[0:1]
	s_cbranch_vccnz .LBB0_428
	s_ashr_i32 s6, s89, 5
	s_add_i32 s0, s6, s81
	s_mul_hi_i32 s1, s0, 0x55555556
	s_lshr_b32 s7, s1, 31
	s_add_i32 s1, s1, s7
	s_mul_i32 s1, s1, 3
	v_lshlrev_b32_e32 v130, 6, v144
	s_sub_i32 s7, s0, s1
	v_and_b32_e32 v136, 0x1ffc0, v130
	s_cmp_eq_u32 s7, 2
	v_lshl_add_u64 v[182:183], v[138:139], 0, v[136:137]
	v_lshl_add_u64 v[180:181], v[140:141], 0, v[136:137]
	v_pk_mul_f32 v[186:187], v[128:129], v[178:179] op_sel_hi:[1,0]
	v_pk_mul_f32 v[188:189], v[126:127], v[178:179] op_sel_hi:[1,0]
	v_pk_mul_f32 v[190:191], v[124:125], v[178:179] op_sel_hi:[1,0]
	s_cselect_b64 s[0:1], -1, 0
	s_cmp_lg_u32 s7, 2
	v_pk_mul_f32 v[192:193], v[122:123], v[178:179] op_sel_hi:[1,0]
	s_cbranch_scc1 .LBB0_397
	v_lshlrev_b32_e32 v252, 6, v144
	v_and_b32_e32 v252, 0x1ffc0, v252
	v_mov_b32_e32 v253, 0
	v_lshl_add_u64 v[254:255], v[138:139], 0, v[252:253]
	global_load_dwordx4 v[238:241], v[254:255], off offset:1040
	global_load_dwordx4 v[242:245], v[254:255], off offset:1024
	v_lshl_add_u64 v[254:255], v[140:141], 0, v[252:253]
	global_load_dwordx4 v[248:251], v[254:255], off offset:1024
	global_load_dwordx4 v[252:255], v[254:255], off offset:1040
	v_mov_b32_e32 v136, v188
	v_mov_b32_e32 v147, v188
	s_nop 1
	v_permlane32_swap_b32_e32 v136, v147
	v_cndmask_b32_e64 v156, v136, v147, s[2:3]
	v_mov_b32_e32 v136, v192
	v_mov_b32_e32 v147, v192
	s_nop 1
	v_permlane32_swap_b32_e32 v136, v147
	v_cndmask_b32_e64 v184, v136, v147, s[2:3]
	v_mov_b32_e32 v136, v189
	v_mov_b32_e32 v147, v189
	s_nop 1
	v_permlane32_swap_b32_e32 v136, v147
	v_cndmask_b32_e64 v157, v136, v147, s[2:3]
	v_mov_b32_e32 v136, v193
	v_mov_b32_e32 v147, v193
	s_nop 1
	v_permlane32_swap_b32_e32 v136, v147
	v_cndmask_b32_e64 v185, v136, v147, s[2:3]
	v_mov_b32_e32 v136, v186
	v_mov_b32_e32 v147, v186
	s_nop 1
	v_permlane32_swap_b32_e32 v136, v147
	v_cndmask_b32_e64 v206, v136, v147, s[2:3]
	v_mov_b32_e32 v136, v190
	v_mov_b32_e32 v147, v190
	s_nop 1
	v_permlane32_swap_b32_e32 v136, v147
	v_cndmask_b32_e64 v222, v136, v147, s[2:3]
	v_mov_b32_e32 v136, v187
	v_mov_b32_e32 v147, v187
	s_nop 1
	v_permlane32_swap_b32_e32 v136, v147
	v_cndmask_b32_e64 v207, v136, v147, s[2:3]
	v_mov_b32_e32 v136, v191
	v_mov_b32_e32 v147, v191
	s_nop 1
	v_permlane32_swap_b32_e32 v136, v147
	v_cndmask_b32_e64 v223, v136, v147, s[2:3]
	s_waitcnt vmcnt(0)
	v_xor_b32_e32 v136, 0x80000000, v252
	v_xor_b32_e32 v147, 0x80000000, v253
	v_xor_b32_e32 v149, 0x80000000, v254
	v_xor_b32_e32 v151, 0x80000000, v255
	v_cndmask_b32_e64 v253, v253, v147, s[2:3]
	v_cndmask_b32_e64 v252, v252, v136, s[2:3]
	v_xor_b32_e32 v136, 0x80000000, v248
	v_xor_b32_e32 v147, 0x80000000, v249
	v_cndmask_b32_e64 v255, v255, v151, s[2:3]
	v_cndmask_b32_e64 v254, v254, v149, s[2:3]
	v_xor_b32_e32 v149, 0x80000000, v250
	v_xor_b32_e32 v151, 0x80000000, v251
	v_cndmask_b32_e64 v249, v249, v147, s[2:3]
	v_cndmask_b32_e64 v248, v248, v136, s[2:3]
	v_cndmask_b32_e64 v251, v251, v151, s[2:3]
	v_cndmask_b32_e64 v250, v250, v149, s[2:3]
	v_pk_mul_f32 v[156:157], v[248:249], v[156:157]
	v_pk_mul_f32 v[206:207], v[250:251], v[206:207]
	v_pk_fma_f32 v[188:189], v[188:189], v[242:243], v[156:157]
	v_pk_mul_f32 v[156:157], v[252:253], v[184:185]
	v_pk_mul_f32 v[184:185], v[254:255], v[222:223]
	v_pk_fma_f32 v[186:187], v[186:187], v[244:245], v[206:207]
	v_pk_fma_f32 v[190:191], v[190:191], v[240:241], v[184:185]
	v_pk_fma_f32 v[192:193], v[192:193], v[238:239], v[156:157]
	v_add_u32_e32 v252, 16, v144
	v_lshlrev_b32_e32 v252, 6, v252
	v_and_b32_e32 v252, 0x1ffc0, v252
	v_mov_b32_e32 v253, 0
	v_lshl_add_u64 v[254:255], v[138:139], 0, v[252:253]
	global_load_dwordx4 v[238:241], v[254:255], off offset:1040
	global_load_dwordx4 v[242:245], v[254:255], off offset:1024
	v_lshl_add_u64 v[254:255], v[140:141], 0, v[252:253]
	global_load_dwordx4 v[248:251], v[254:255], off offset:1024
	global_load_dwordx4 v[252:255], v[254:255], off offset:1040
.LBB0_397:
	v_readlane_b32 s8, v247, 37
	v_ashrrev_i32_e32 v147, 31, v146
	v_readlane_b32 s9, v247, 38
	v_readlane_b32 s7, v247, 18
	s_add_i32 s6, s7, s6
	v_lshl_add_u64 v[156:157], v[146:147], 1, s[8:9]
	v_mad_i64_i32 v[184:185], s[8:9], v144, s87, v[156:157]
	s_mul_hi_i32 s7, s6, 0x55555556
	s_lshr_b32 s8, s7, 31
	s_add_i32 s7, s7, s8
	s_mul_i32 s7, s7, 3
	v_cvt_pk_bf16_f32 v130, v188, v189
	v_cvt_pk_bf16_f32 v131, v186, v187
	v_cvt_pk_bf16_f32 v132, v192, v193
	v_cvt_pk_bf16_f32 v133, v190, v191
	s_sub_i32 s6, s6, s7
	v_mov_b32_e32 v179, v178
	global_store_dwordx4 v[184:185], v[130:133], off
	s_cmp_eq_u32 s6, 2
	v_pk_mul_f32 v[188:189], v[110:111], v[178:179]
	v_mov_b32_e32 v130, v178
	v_mov_b32_e32 v131, v178
	v_pk_mul_f32 v[186:187], v[112:113], v[130:131]
	v_pk_mul_f32 v[190:191], v[108:109], v[130:131]
	s_cselect_b64 s[56:57], -1, 0
	s_cmp_lg_u32 s6, 2
	v_pk_mul_f32 v[178:179], v[106:107], v[178:179]
	s_cbranch_scc1 .LBB0_399
	v_lshlrev_b32_e32 v252, 6, v144
	v_and_b32_e32 v252, 0x1ffc0, v252
	v_mov_b32_e32 v253, 0
	v_lshl_add_u64 v[254:255], v[138:139], 0, v[252:253]
	global_load_dwordx4 v[238:241], v[254:255], off offset:1040
	global_load_dwordx4 v[242:245], v[254:255], off offset:1024
	v_lshl_add_u64 v[254:255], v[140:141], 0, v[252:253]
	global_load_dwordx4 v[248:251], v[254:255], off offset:1024
	global_load_dwordx4 v[252:255], v[254:255], off offset:1040
	v_mov_b32_e32 v136, v188
	v_mov_b32_e32 v147, v188
	s_nop 1
	v_permlane32_swap_b32_e32 v136, v147
	v_cndmask_b32_e64 v192, v136, v147, s[2:3]
	v_mov_b32_e32 v136, v178
	v_mov_b32_e32 v147, v178
	s_nop 1
	v_permlane32_swap_b32_e32 v136, v147
	v_cndmask_b32_e64 v206, v136, v147, s[2:3]
	v_mov_b32_e32 v136, v189
	v_mov_b32_e32 v147, v189
	s_nop 1
	v_permlane32_swap_b32_e32 v136, v147
	v_cndmask_b32_e64 v193, v136, v147, s[2:3]
	v_mov_b32_e32 v136, v179
	v_mov_b32_e32 v147, v179
	s_nop 1
	v_permlane32_swap_b32_e32 v136, v147
	v_cndmask_b32_e64 v207, v136, v147, s[2:3]
	v_mov_b32_e32 v136, v186
	v_mov_b32_e32 v147, v186
	s_nop 1
	v_permlane32_swap_b32_e32 v136, v147
	v_cndmask_b32_e64 v218, v136, v147, s[2:3]
	v_mov_b32_e32 v136, v190
	v_mov_b32_e32 v147, v190
	s_nop 1
	v_permlane32_swap_b32_e32 v136, v147
	v_cndmask_b32_e64 v220, v136, v147, s[2:3]
	v_mov_b32_e32 v136, v187
	v_mov_b32_e32 v147, v187
	s_nop 1
	v_permlane32_swap_b32_e32 v136, v147
	v_cndmask_b32_e64 v219, v136, v147, s[2:3]
	v_mov_b32_e32 v136, v191
	v_mov_b32_e32 v147, v191
	s_nop 1
	v_permlane32_swap_b32_e32 v136, v147
	v_cndmask_b32_e64 v221, v136, v147, s[2:3]
	s_waitcnt vmcnt(0)
	v_xor_b32_e32 v136, 0x80000000, v252
	v_xor_b32_e32 v147, 0x80000000, v253
	v_xor_b32_e32 v149, 0x80000000, v254
	v_xor_b32_e32 v151, 0x80000000, v255
	v_cndmask_b32_e64 v255, v255, v151, s[2:3]
	v_cndmask_b32_e64 v254, v254, v149, s[2:3]
	v_cndmask_b32_e64 v253, v253, v147, s[2:3]
	v_cndmask_b32_e64 v252, v252, v136, s[2:3]
	v_xor_b32_e32 v136, 0x80000000, v248
	v_xor_b32_e32 v147, 0x80000000, v249
	v_xor_b32_e32 v149, 0x80000000, v250
	v_xor_b32_e32 v151, 0x80000000, v251
	v_cndmask_b32_e64 v251, v251, v151, s[2:3]
	v_cndmask_b32_e64 v250, v250, v149, s[2:3]
	v_cndmask_b32_e64 v249, v249, v147, s[2:3]
	v_cndmask_b32_e64 v248, v248, v136, s[2:3]
	v_pk_mul_f32 v[192:193], v[248:249], v[192:193]
	v_pk_mul_f32 v[248:249], v[250:251], v[218:219]
	v_pk_mul_f32 v[252:253], v[252:253], v[206:207]
	v_pk_mul_f32 v[254:255], v[254:255], v[220:221]
	v_pk_fma_f32 v[186:187], v[186:187], v[244:245], v[248:249]
	v_pk_fma_f32 v[188:189], v[188:189], v[242:243], v[192:193]
	v_pk_fma_f32 v[190:191], v[190:191], v[240:241], v[254:255]
	v_pk_fma_f32 v[178:179], v[178:179], v[238:239], v[252:253]
	v_add_u32_e32 v252, 16, v144
	v_lshlrev_b32_e32 v252, 6, v252
	v_and_b32_e32 v252, 0x1ffc0, v252
	v_mov_b32_e32 v253, 0
	v_lshl_add_u64 v[254:255], v[138:139], 0, v[252:253]
	global_load_dwordx4 v[238:241], v[254:255], off offset:1040
	global_load_dwordx4 v[242:245], v[254:255], off offset:1024
	v_lshl_add_u64 v[254:255], v[140:141], 0, v[252:253]
	global_load_dwordx4 v[248:251], v[254:255], off offset:1024
	global_load_dwordx4 v[252:255], v[254:255], off offset:1040
.LBB0_399:
	v_cvt_pk_bf16_f32 v130, v188, v189
	v_cvt_pk_bf16_f32 v131, v186, v187
	v_cvt_pk_bf16_f32 v132, v178, v179
	v_cvt_pk_bf16_f32 v133, v190, v191
	global_store_dwordx4 v[184:185], v[130:133], off offset:256
	v_pk_mul_f32 v[182:183], v[120:121], v[176:177] op_sel_hi:[1,0]
	v_pk_mul_f32 v[184:185], v[118:119], v[176:177] op_sel_hi:[1,0]
	v_lshlrev_b32_e32 v130, 6, v174
	v_and_b32_e32 v136, 0x1ffc0, v130
	v_cndmask_b32_e64 v130, 0, 1, s[0:1]
	v_lshl_add_u64 v[180:181], v[138:139], 0, v[136:137]
	v_lshl_add_u64 v[178:179], v[140:141], 0, v[136:137]
	v_pk_mul_f32 v[186:187], v[116:117], v[176:177] op_sel_hi:[1,0]
	v_cmp_ne_u32_e64 s[6:7], 1, v130
	s_andn2_b64 vcc, exec, s[0:1]
	v_pk_mul_f32 v[188:189], v[114:115], v[176:177] op_sel_hi:[1,0]
	s_cbranch_vccnz .LBB0_401
	v_mov_b32_e32 v136, v184
	v_mov_b32_e32 v147, v184
	s_nop 1
	v_permlane32_swap_b32_e32 v136, v147
	v_cndmask_b32_e64 v206, v136, v147, s[2:3]
	v_mov_b32_e32 v136, v188
	v_mov_b32_e32 v147, v188
	s_nop 1
	v_permlane32_swap_b32_e32 v136, v147
	v_cndmask_b32_e64 v218, v136, v147, s[2:3]
	v_mov_b32_e32 v136, v185
	v_mov_b32_e32 v147, v185
	s_nop 1
	v_permlane32_swap_b32_e32 v136, v147
	v_cndmask_b32_e64 v207, v136, v147, s[2:3]
	v_mov_b32_e32 v136, v189
	v_mov_b32_e32 v147, v189
	s_nop 1
	v_permlane32_swap_b32_e32 v136, v147
	v_cndmask_b32_e64 v219, v136, v147, s[2:3]
	v_mov_b32_e32 v136, v182
	v_mov_b32_e32 v147, v182
	s_nop 1
	v_permlane32_swap_b32_e32 v136, v147
	v_cndmask_b32_e64 v220, v136, v147, s[2:3]
	v_mov_b32_e32 v136, v186
	v_mov_b32_e32 v147, v186
	s_nop 1
	v_permlane32_swap_b32_e32 v136, v147
	v_cndmask_b32_e64 v222, v136, v147, s[2:3]
	v_mov_b32_e32 v136, v183
	v_mov_b32_e32 v147, v183
	s_nop 1
	v_permlane32_swap_b32_e32 v136, v147
	v_cndmask_b32_e64 v221, v136, v147, s[2:3]
	v_mov_b32_e32 v136, v187
	v_mov_b32_e32 v147, v187
	s_nop 1
	v_permlane32_swap_b32_e32 v136, v147
	v_cndmask_b32_e64 v223, v136, v147, s[2:3]
	s_waitcnt vmcnt(2)
	v_xor_b32_e32 v136, 0x80000000, v252
	v_xor_b32_e32 v147, 0x80000000, v253
	v_xor_b32_e32 v149, 0x80000000, v254
	v_xor_b32_e32 v151, 0x80000000, v255
	v_cndmask_b32_e64 v255, v255, v151, s[2:3]
	v_cndmask_b32_e64 v254, v254, v149, s[2:3]
	v_cndmask_b32_e64 v253, v253, v147, s[2:3]
	v_cndmask_b32_e64 v252, v252, v136, s[2:3]
	v_xor_b32_e32 v136, 0x80000000, v248
	v_xor_b32_e32 v147, 0x80000000, v249
	v_xor_b32_e32 v149, 0x80000000, v250
	v_xor_b32_e32 v151, 0x80000000, v251
	v_cndmask_b32_e64 v251, v251, v151, s[2:3]
	v_cndmask_b32_e64 v250, v250, v149, s[2:3]
	v_cndmask_b32_e64 v249, v249, v147, s[2:3]
	v_cndmask_b32_e64 v248, v248, v136, s[2:3]
	v_pk_mul_f32 v[206:207], v[248:249], v[206:207]
	v_pk_mul_f32 v[248:249], v[250:251], v[220:221]
	v_pk_fma_f32 v[184:185], v[184:185], v[242:243], v[206:207]
	v_pk_fma_f32 v[182:183], v[182:183], v[244:245], v[248:249]
	v_pk_mul_f32 v[242:243], v[252:253], v[218:219]
	v_pk_mul_f32 v[244:245], v[254:255], v[222:223]
	v_pk_fma_f32 v[188:189], v[188:189], v[238:239], v[242:243]
	v_pk_fma_f32 v[186:187], v[186:187], v[240:241], v[244:245]
	v_add_u32_e32 v252, 32, v144
	v_lshlrev_b32_e32 v252, 6, v252
	v_and_b32_e32 v252, 0x1ffc0, v252
	v_mov_b32_e32 v253, 0
	v_lshl_add_u64 v[254:255], v[138:139], 0, v[252:253]
	global_load_dwordx4 v[238:241], v[254:255], off offset:1040
	global_load_dwordx4 v[242:245], v[254:255], off offset:1024
	v_lshl_add_u64 v[254:255], v[140:141], 0, v[252:253]
	global_load_dwordx4 v[248:251], v[254:255], off offset:1024
	global_load_dwordx4 v[252:255], v[254:255], off offset:1040
.LBB0_401:
	v_mad_i64_i32 v[174:175], s[0:1], v174, s87, v[156:157]
	v_cvt_pk_bf16_f32 v130, v184, v185
	v_cvt_pk_bf16_f32 v131, v182, v183
	v_cvt_pk_bf16_f32 v132, v188, v189
	v_cvt_pk_bf16_f32 v133, v186, v187
	global_store_dwordx4 v[174:175], v[130:133], off
	v_mov_b32_e32 v177, v176
	v_pk_mul_f32 v[184:185], v[94:95], v[176:177]
	v_mov_b32_e32 v130, v176
	v_mov_b32_e32 v131, v176
	v_pk_mul_f32 v[182:183], v[96:97], v[130:131]
	v_pk_mul_f32 v[186:187], v[92:93], v[130:131]
	v_cndmask_b32_e64 v130, 0, 1, s[56:57]
	v_cmp_ne_u32_e64 s[8:9], 1, v130
	s_andn2_b64 vcc, exec, s[56:57]
	v_pk_mul_f32 v[176:177], v[90:91], v[176:177]
	s_cbranch_vccnz .LBB0_403
	v_mov_b32_e32 v136, v184
	v_mov_b32_e32 v147, v184
	s_nop 1
	v_permlane32_swap_b32_e32 v136, v147
	v_cndmask_b32_e64 v192, v136, v147, s[2:3]
	v_mov_b32_e32 v136, v176
	v_mov_b32_e32 v147, v176
	s_nop 1
	v_permlane32_swap_b32_e32 v136, v147
	v_cndmask_b32_e64 v206, v136, v147, s[2:3]
	v_mov_b32_e32 v136, v185
	v_mov_b32_e32 v147, v185
	s_nop 1
	v_permlane32_swap_b32_e32 v136, v147
	v_cndmask_b32_e64 v193, v136, v147, s[2:3]
	v_mov_b32_e32 v136, v177
	v_mov_b32_e32 v147, v177
	s_nop 1
	v_permlane32_swap_b32_e32 v136, v147
	v_cndmask_b32_e64 v207, v136, v147, s[2:3]
	v_mov_b32_e32 v136, v182
	v_mov_b32_e32 v147, v182
	s_nop 1
	v_permlane32_swap_b32_e32 v136, v147
	v_cndmask_b32_e64 v214, v136, v147, s[2:3]
	v_mov_b32_e32 v136, v186
	v_mov_b32_e32 v147, v186
	s_nop 1
	v_permlane32_swap_b32_e32 v136, v147
	v_cndmask_b32_e64 v216, v136, v147, s[2:3]
	v_mov_b32_e32 v136, v183
	v_mov_b32_e32 v147, v183
	s_nop 1
	v_permlane32_swap_b32_e32 v136, v147
	v_cndmask_b32_e64 v215, v136, v147, s[2:3]
	v_mov_b32_e32 v136, v187
	v_mov_b32_e32 v147, v187
	s_nop 1
	v_permlane32_swap_b32_e32 v136, v147
	v_cndmask_b32_e64 v217, v136, v147, s[2:3]
	s_waitcnt vmcnt(2)
	v_xor_b32_e32 v136, 0x80000000, v252
	v_xor_b32_e32 v147, 0x80000000, v253
	v_xor_b32_e32 v149, 0x80000000, v254
	v_xor_b32_e32 v151, 0x80000000, v255
	v_cndmask_b32_e64 v255, v255, v151, s[2:3]
	v_cndmask_b32_e64 v254, v254, v149, s[2:3]
	v_cndmask_b32_e64 v253, v253, v147, s[2:3]
	v_cndmask_b32_e64 v252, v252, v136, s[2:3]
	v_xor_b32_e32 v136, 0x80000000, v248
	v_xor_b32_e32 v147, 0x80000000, v249
	v_xor_b32_e32 v149, 0x80000000, v250
	v_xor_b32_e32 v151, 0x80000000, v251
	v_cndmask_b32_e64 v251, v251, v151, s[2:3]
	v_cndmask_b32_e64 v250, v250, v149, s[2:3]
	v_cndmask_b32_e64 v249, v249, v147, s[2:3]
	v_cndmask_b32_e64 v248, v248, v136, s[2:3]
	v_pk_mul_f32 v[192:193], v[248:249], v[192:193]
	v_pk_mul_f32 v[248:249], v[250:251], v[214:215]
	v_pk_mul_f32 v[252:253], v[252:253], v[206:207]
	v_pk_mul_f32 v[254:255], v[254:255], v[216:217]
	v_pk_fma_f32 v[182:183], v[182:183], v[244:245], v[248:249]
	v_pk_fma_f32 v[184:185], v[184:185], v[242:243], v[192:193]
	v_pk_fma_f32 v[186:187], v[186:187], v[240:241], v[254:255]
	v_pk_fma_f32 v[176:177], v[176:177], v[238:239], v[252:253]
	v_add_u32_e32 v252, 32, v144
	v_lshlrev_b32_e32 v252, 6, v252
	v_and_b32_e32 v252, 0x1ffc0, v252
	v_mov_b32_e32 v253, 0
	v_lshl_add_u64 v[254:255], v[138:139], 0, v[252:253]
	global_load_dwordx4 v[238:241], v[254:255], off offset:1040
	global_load_dwordx4 v[242:245], v[254:255], off offset:1024
	v_lshl_add_u64 v[254:255], v[140:141], 0, v[252:253]
	global_load_dwordx4 v[248:251], v[254:255], off offset:1024
	global_load_dwordx4 v[252:255], v[254:255], off offset:1040
.LBB0_403:
	v_cvt_pk_bf16_f32 v130, v184, v185
	v_cvt_pk_bf16_f32 v131, v182, v183
	v_cvt_pk_bf16_f32 v132, v176, v177
	v_cvt_pk_bf16_f32 v133, v186, v187
	global_store_dwordx4 v[174:175], v[130:133], off offset:256
	v_pk_mul_f32 v[178:179], v[104:105], v[172:173] op_sel_hi:[1,0]
	v_pk_mul_f32 v[180:181], v[102:103], v[172:173] op_sel_hi:[1,0]
	v_lshlrev_b32_e32 v130, 6, v170
	v_and_b32_e32 v136, 0x1ffc0, v130
	v_lshl_add_u64 v[176:177], v[138:139], 0, v[136:137]
	v_lshl_add_u64 v[174:175], v[140:141], 0, v[136:137]
	v_pk_mul_f32 v[182:183], v[100:101], v[172:173] op_sel_hi:[1,0]
	s_and_b64 vcc, exec, s[6:7]
	v_pk_mul_f32 v[184:185], v[98:99], v[172:173] op_sel_hi:[1,0]
	s_cbranch_vccnz .LBB0_405
	v_mov_b32_e32 v136, v180
	v_mov_b32_e32 v147, v180
	s_nop 1
	v_permlane32_swap_b32_e32 v136, v147
	v_cndmask_b32_e64 v206, v136, v147, s[2:3]
	v_mov_b32_e32 v136, v184
	v_mov_b32_e32 v147, v184
	s_nop 1
	v_permlane32_swap_b32_e32 v136, v147
	v_cndmask_b32_e64 v214, v136, v147, s[2:3]
	v_mov_b32_e32 v136, v181
	v_mov_b32_e32 v147, v181
	s_nop 1
	v_permlane32_swap_b32_e32 v136, v147
	v_cndmask_b32_e64 v207, v136, v147, s[2:3]
	v_mov_b32_e32 v136, v185
	v_mov_b32_e32 v147, v185
	s_nop 1
	v_permlane32_swap_b32_e32 v136, v147
	v_cndmask_b32_e64 v215, v136, v147, s[2:3]
	v_mov_b32_e32 v136, v178
	v_mov_b32_e32 v147, v178
	s_nop 1
	v_permlane32_swap_b32_e32 v136, v147
	v_cndmask_b32_e64 v216, v136, v147, s[2:3]
	v_mov_b32_e32 v136, v182
	v_mov_b32_e32 v147, v182
	s_nop 1
	v_permlane32_swap_b32_e32 v136, v147
	v_cndmask_b32_e64 v218, v136, v147, s[2:3]
	v_mov_b32_e32 v136, v179
	v_mov_b32_e32 v147, v179
	s_nop 1
	v_permlane32_swap_b32_e32 v136, v147
	v_cndmask_b32_e64 v217, v136, v147, s[2:3]
	v_mov_b32_e32 v136, v183
	v_mov_b32_e32 v147, v183
	s_nop 1
	v_permlane32_swap_b32_e32 v136, v147
	v_cndmask_b32_e64 v219, v136, v147, s[2:3]
	s_waitcnt vmcnt(2)
	v_xor_b32_e32 v136, 0x80000000, v252
	v_xor_b32_e32 v147, 0x80000000, v253
	v_xor_b32_e32 v149, 0x80000000, v254
	v_xor_b32_e32 v151, 0x80000000, v255
	v_cndmask_b32_e64 v255, v255, v151, s[2:3]
	v_cndmask_b32_e64 v254, v254, v149, s[2:3]
	v_cndmask_b32_e64 v253, v253, v147, s[2:3]
	v_cndmask_b32_e64 v252, v252, v136, s[2:3]
	v_xor_b32_e32 v136, 0x80000000, v248
	v_xor_b32_e32 v147, 0x80000000, v249
	v_xor_b32_e32 v149, 0x80000000, v250
	v_xor_b32_e32 v151, 0x80000000, v251
	v_cndmask_b32_e64 v251, v251, v151, s[2:3]
	v_cndmask_b32_e64 v250, v250, v149, s[2:3]
	v_cndmask_b32_e64 v249, v249, v147, s[2:3]
	v_cndmask_b32_e64 v248, v248, v136, s[2:3]
	v_pk_mul_f32 v[248:249], v[248:249], v[206:207]
	v_pk_mul_f32 v[250:251], v[250:251], v[216:217]
	v_pk_fma_f32 v[180:181], v[180:181], v[242:243], v[248:249]
	v_pk_fma_f32 v[178:179], v[178:179], v[244:245], v[250:251]
	v_pk_mul_f32 v[242:243], v[252:253], v[214:215]
	v_pk_mul_f32 v[244:245], v[254:255], v[218:219]
	v_pk_fma_f32 v[184:185], v[184:185], v[238:239], v[242:243]
	v_pk_fma_f32 v[182:183], v[182:183], v[240:241], v[244:245]
	v_add_u32_e32 v252, 48, v144
	v_lshlrev_b32_e32 v252, 6, v252
	v_and_b32_e32 v252, 0x1ffc0, v252
	v_mov_b32_e32 v253, 0
	v_lshl_add_u64 v[254:255], v[138:139], 0, v[252:253]
	global_load_dwordx4 v[238:241], v[254:255], off offset:1040
	global_load_dwordx4 v[242:245], v[254:255], off offset:1024
	v_lshl_add_u64 v[254:255], v[140:141], 0, v[252:253]
	global_load_dwordx4 v[248:251], v[254:255], off offset:1024
	global_load_dwordx4 v[252:255], v[254:255], off offset:1040
.LBB0_405:
	v_mad_i64_i32 v[170:171], s[0:1], v170, s87, v[156:157]
	v_cvt_pk_bf16_f32 v130, v180, v181
	v_cvt_pk_bf16_f32 v131, v178, v179
	v_cvt_pk_bf16_f32 v132, v184, v185
	v_cvt_pk_bf16_f32 v133, v182, v183
	v_mov_b32_e32 v173, v172
	global_store_dwordx4 v[170:171], v[130:133], off
	v_pk_mul_f32 v[180:181], v[78:79], v[172:173]
	s_and_b64 vcc, exec, s[8:9]
	v_mov_b32_e32 v130, v172
	v_mov_b32_e32 v131, v172
	v_pk_mul_f32 v[178:179], v[80:81], v[130:131]
	v_pk_mul_f32 v[182:183], v[76:77], v[130:131]
	v_pk_mul_f32 v[172:173], v[74:75], v[172:173]
	s_cbranch_vccnz .LBB0_407
	v_mov_b32_e32 v136, v180
	v_mov_b32_e32 v147, v180
	s_nop 1
	v_permlane32_swap_b32_e32 v136, v147
	v_cndmask_b32_e64 v192, v136, v147, s[2:3]
	v_mov_b32_e32 v136, v172
	v_mov_b32_e32 v147, v172
	s_nop 1
	v_permlane32_swap_b32_e32 v136, v147
	v_cndmask_b32_e64 v206, v136, v147, s[2:3]
	v_mov_b32_e32 v136, v181
	v_mov_b32_e32 v147, v181
	s_nop 1
	v_permlane32_swap_b32_e32 v136, v147
	v_cndmask_b32_e64 v193, v136, v147, s[2:3]
	v_mov_b32_e32 v136, v173
	v_mov_b32_e32 v147, v173
	s_nop 1
	v_permlane32_swap_b32_e32 v136, v147
	v_cndmask_b32_e64 v207, v136, v147, s[2:3]
	v_mov_b32_e32 v136, v178
	v_mov_b32_e32 v147, v178
	s_nop 1
	v_permlane32_swap_b32_e32 v136, v147
	v_cndmask_b32_e64 v210, v136, v147, s[2:3]
	v_mov_b32_e32 v136, v182
	v_mov_b32_e32 v147, v182
	s_nop 1
	v_permlane32_swap_b32_e32 v136, v147
	v_cndmask_b32_e64 v212, v136, v147, s[2:3]
	v_mov_b32_e32 v136, v179
	v_mov_b32_e32 v147, v179
	s_nop 1
	v_permlane32_swap_b32_e32 v136, v147
	v_cndmask_b32_e64 v211, v136, v147, s[2:3]
	v_mov_b32_e32 v136, v183
	v_mov_b32_e32 v147, v183
	s_nop 1
	v_permlane32_swap_b32_e32 v136, v147
	v_cndmask_b32_e64 v213, v136, v147, s[2:3]
	s_waitcnt vmcnt(2)
	v_xor_b32_e32 v136, 0x80000000, v252
	v_xor_b32_e32 v147, 0x80000000, v253
	v_xor_b32_e32 v149, 0x80000000, v254
	v_xor_b32_e32 v151, 0x80000000, v255
	v_cndmask_b32_e64 v255, v255, v151, s[2:3]
	v_cndmask_b32_e64 v254, v254, v149, s[2:3]
	v_cndmask_b32_e64 v253, v253, v147, s[2:3]
	v_cndmask_b32_e64 v252, v252, v136, s[2:3]
	v_xor_b32_e32 v136, 0x80000000, v248
	v_xor_b32_e32 v147, 0x80000000, v249
	v_xor_b32_e32 v149, 0x80000000, v250
	v_xor_b32_e32 v151, 0x80000000, v251
	v_cndmask_b32_e64 v251, v251, v151, s[2:3]
	v_cndmask_b32_e64 v250, v250, v149, s[2:3]
	v_cndmask_b32_e64 v249, v249, v147, s[2:3]
	v_cndmask_b32_e64 v248, v248, v136, s[2:3]
	v_pk_mul_f32 v[248:249], v[248:249], v[192:193]
	v_pk_mul_f32 v[250:251], v[250:251], v[210:211]
	v_pk_mul_f32 v[252:253], v[252:253], v[206:207]
	v_pk_mul_f32 v[254:255], v[254:255], v[212:213]
	v_pk_fma_f32 v[178:179], v[178:179], v[244:245], v[250:251]
	v_pk_fma_f32 v[180:181], v[180:181], v[242:243], v[248:249]
	v_pk_fma_f32 v[182:183], v[182:183], v[240:241], v[254:255]
	v_pk_fma_f32 v[172:173], v[172:173], v[238:239], v[252:253]
	v_add_u32_e32 v252, 48, v144
	v_lshlrev_b32_e32 v252, 6, v252
	v_and_b32_e32 v252, 0x1ffc0, v252
	v_mov_b32_e32 v253, 0
	v_lshl_add_u64 v[254:255], v[138:139], 0, v[252:253]
	global_load_dwordx4 v[238:241], v[254:255], off offset:1040
	global_load_dwordx4 v[242:245], v[254:255], off offset:1024
	v_lshl_add_u64 v[254:255], v[140:141], 0, v[252:253]
	global_load_dwordx4 v[248:251], v[254:255], off offset:1024
	global_load_dwordx4 v[252:255], v[254:255], off offset:1040
.LBB0_407:
	v_cvt_pk_bf16_f32 v130, v180, v181
	v_cvt_pk_bf16_f32 v131, v178, v179
	v_cvt_pk_bf16_f32 v132, v172, v173
	v_cvt_pk_bf16_f32 v133, v182, v183
	global_store_dwordx4 v[170:171], v[130:133], off offset:256
	v_pk_mul_f32 v[174:175], v[88:89], v[168:169] op_sel_hi:[1,0]
	v_pk_mul_f32 v[176:177], v[86:87], v[168:169] op_sel_hi:[1,0]
	v_lshlrev_b32_e32 v130, 6, v166
	v_and_b32_e32 v136, 0x1ffc0, v130
	v_lshl_add_u64 v[172:173], v[138:139], 0, v[136:137]
	v_lshl_add_u64 v[170:171], v[140:141], 0, v[136:137]
	v_pk_mul_f32 v[178:179], v[84:85], v[168:169] op_sel_hi:[1,0]
	s_and_b64 vcc, exec, s[6:7]
	v_pk_mul_f32 v[180:181], v[82:83], v[168:169] op_sel_hi:[1,0]
	s_cbranch_vccnz .LBB0_409
	v_mov_b32_e32 v136, v176
	v_mov_b32_e32 v147, v176
	s_nop 1
	v_permlane32_swap_b32_e32 v136, v147
	v_cndmask_b32_e64 v206, v136, v147, s[2:3]
	v_mov_b32_e32 v136, v180
	v_mov_b32_e32 v147, v180
	s_nop 1
	v_permlane32_swap_b32_e32 v136, v147
	v_cndmask_b32_e64 v210, v136, v147, s[2:3]
	v_mov_b32_e32 v136, v177
	v_mov_b32_e32 v147, v177
	s_nop 1
	v_permlane32_swap_b32_e32 v136, v147
	v_cndmask_b32_e64 v207, v136, v147, s[2:3]
	v_mov_b32_e32 v136, v181
	v_mov_b32_e32 v147, v181
	s_nop 1
	v_permlane32_swap_b32_e32 v136, v147
	v_cndmask_b32_e64 v211, v136, v147, s[2:3]
	v_mov_b32_e32 v136, v174
	v_mov_b32_e32 v147, v174
	s_nop 1
	v_permlane32_swap_b32_e32 v136, v147
	v_cndmask_b32_e64 v212, v136, v147, s[2:3]
	v_mov_b32_e32 v136, v178
	v_mov_b32_e32 v147, v178
	s_nop 1
	v_permlane32_swap_b32_e32 v136, v147
	v_cndmask_b32_e64 v214, v136, v147, s[2:3]
	v_mov_b32_e32 v136, v175
	v_mov_b32_e32 v147, v175
	s_nop 1
	v_permlane32_swap_b32_e32 v136, v147
	v_cndmask_b32_e64 v213, v136, v147, s[2:3]
	v_mov_b32_e32 v136, v179
	v_mov_b32_e32 v147, v179
	s_nop 1
	v_permlane32_swap_b32_e32 v136, v147
	v_cndmask_b32_e64 v215, v136, v147, s[2:3]
	s_waitcnt vmcnt(2)
	v_xor_b32_e32 v136, 0x80000000, v252
	v_xor_b32_e32 v147, 0x80000000, v253
	v_xor_b32_e32 v149, 0x80000000, v254
	v_xor_b32_e32 v151, 0x80000000, v255
	v_cndmask_b32_e64 v255, v255, v151, s[2:3]
	v_cndmask_b32_e64 v254, v254, v149, s[2:3]
	v_cndmask_b32_e64 v253, v253, v147, s[2:3]
	v_cndmask_b32_e64 v252, v252, v136, s[2:3]
	v_xor_b32_e32 v136, 0x80000000, v248
	v_xor_b32_e32 v147, 0x80000000, v249
	v_xor_b32_e32 v149, 0x80000000, v250
	v_xor_b32_e32 v151, 0x80000000, v251
	v_cndmask_b32_e64 v251, v251, v151, s[2:3]
	v_cndmask_b32_e64 v250, v250, v149, s[2:3]
	v_cndmask_b32_e64 v249, v249, v147, s[2:3]
	v_cndmask_b32_e64 v248, v248, v136, s[2:3]
	v_pk_mul_f32 v[248:249], v[248:249], v[206:207]
	v_pk_mul_f32 v[250:251], v[250:251], v[212:213]
	v_pk_fma_f32 v[176:177], v[176:177], v[242:243], v[248:249]
	v_pk_fma_f32 v[174:175], v[174:175], v[244:245], v[250:251]
	v_pk_mul_f32 v[242:243], v[252:253], v[210:211]
	v_pk_mul_f32 v[244:245], v[254:255], v[214:215]
	v_pk_fma_f32 v[180:181], v[180:181], v[238:239], v[242:243]
	v_pk_fma_f32 v[178:179], v[178:179], v[240:241], v[244:245]
	v_add_u32_e32 v252, 128, v144
	v_lshlrev_b32_e32 v252, 6, v252
	v_and_b32_e32 v252, 0x1ffc0, v252
	v_mov_b32_e32 v253, 0
	v_lshl_add_u64 v[254:255], v[138:139], 0, v[252:253]
	global_load_dwordx4 v[238:241], v[254:255], off offset:1040
	global_load_dwordx4 v[242:245], v[254:255], off offset:1024
	v_lshl_add_u64 v[254:255], v[140:141], 0, v[252:253]
	global_load_dwordx4 v[248:251], v[254:255], off offset:1024
	global_load_dwordx4 v[252:255], v[254:255], off offset:1040
.LBB0_409:
	v_mad_i64_i32 v[166:167], s[0:1], v166, s87, v[156:157]
	v_cvt_pk_bf16_f32 v130, v176, v177
	v_cvt_pk_bf16_f32 v131, v174, v175
	v_cvt_pk_bf16_f32 v132, v180, v181
	v_cvt_pk_bf16_f32 v133, v178, v179
	v_mov_b32_e32 v169, v168
	global_store_dwordx4 v[166:167], v[130:133], off
	v_pk_mul_f32 v[176:177], v[70:71], v[168:169]
	s_and_b64 vcc, exec, s[8:9]
	v_mov_b32_e32 v130, v168
	v_mov_b32_e32 v131, v168
	v_pk_mul_f32 v[174:175], v[72:73], v[130:131]
	v_pk_mul_f32 v[178:179], v[68:69], v[130:131]
	v_pk_mul_f32 v[168:169], v[66:67], v[168:169]
	s_cbranch_vccnz .LBB0_411
	v_mov_b32_e32 v136, v176
	v_mov_b32_e32 v147, v176
	s_nop 1
	v_permlane32_swap_b32_e32 v136, v147
	v_cndmask_b32_e64 v188, v136, v147, s[2:3]
	v_mov_b32_e32 v136, v168
	v_mov_b32_e32 v147, v168
	s_nop 1
	v_permlane32_swap_b32_e32 v136, v147
	v_cndmask_b32_e64 v190, v136, v147, s[2:3]
	v_mov_b32_e32 v136, v177
	v_mov_b32_e32 v147, v177
	s_nop 1
	v_permlane32_swap_b32_e32 v136, v147
	v_cndmask_b32_e64 v189, v136, v147, s[2:3]
	v_mov_b32_e32 v136, v169
	v_mov_b32_e32 v147, v169
	s_nop 1
	v_permlane32_swap_b32_e32 v136, v147
	v_cndmask_b32_e64 v191, v136, v147, s[2:3]
	v_mov_b32_e32 v136, v174
	v_mov_b32_e32 v147, v174
	s_nop 1
	v_permlane32_swap_b32_e32 v136, v147
	v_cndmask_b32_e64 v192, v136, v147, s[2:3]
	v_mov_b32_e32 v136, v178
	v_mov_b32_e32 v147, v178
	s_nop 1
	v_permlane32_swap_b32_e32 v136, v147
	v_cndmask_b32_e64 v206, v136, v147, s[2:3]
	v_mov_b32_e32 v136, v175
	v_mov_b32_e32 v147, v175
	s_nop 1
	v_permlane32_swap_b32_e32 v136, v147
	v_cndmask_b32_e64 v193, v136, v147, s[2:3]
	v_mov_b32_e32 v136, v179
	v_mov_b32_e32 v147, v179
	s_nop 1
	v_permlane32_swap_b32_e32 v136, v147
	v_cndmask_b32_e64 v207, v136, v147, s[2:3]
	s_waitcnt vmcnt(2)
	v_xor_b32_e32 v136, 0x80000000, v252
	v_xor_b32_e32 v147, 0x80000000, v253
	v_xor_b32_e32 v149, 0x80000000, v254
	v_xor_b32_e32 v151, 0x80000000, v255
	v_cndmask_b32_e64 v255, v255, v151, s[2:3]
	v_cndmask_b32_e64 v254, v254, v149, s[2:3]
	v_cndmask_b32_e64 v253, v253, v147, s[2:3]
	v_cndmask_b32_e64 v252, v252, v136, s[2:3]
	v_xor_b32_e32 v136, 0x80000000, v248
	v_xor_b32_e32 v147, 0x80000000, v249
	v_xor_b32_e32 v149, 0x80000000, v250
	v_xor_b32_e32 v151, 0x80000000, v251
	v_cndmask_b32_e64 v251, v251, v151, s[2:3]
	v_cndmask_b32_e64 v250, v250, v149, s[2:3]
	v_cndmask_b32_e64 v249, v249, v147, s[2:3]
	v_cndmask_b32_e64 v248, v248, v136, s[2:3]
	v_pk_mul_f32 v[248:249], v[248:249], v[188:189]
	v_pk_mul_f32 v[250:251], v[250:251], v[192:193]
	v_pk_mul_f32 v[252:253], v[252:253], v[190:191]
	v_pk_mul_f32 v[254:255], v[254:255], v[206:207]
	v_pk_fma_f32 v[174:175], v[174:175], v[244:245], v[250:251]
	v_pk_fma_f32 v[176:177], v[176:177], v[242:243], v[248:249]
	v_pk_fma_f32 v[178:179], v[178:179], v[240:241], v[254:255]
	v_pk_fma_f32 v[168:169], v[168:169], v[238:239], v[252:253]
	v_add_u32_e32 v252, 128, v144
	v_lshlrev_b32_e32 v252, 6, v252
	v_and_b32_e32 v252, 0x1ffc0, v252
	v_mov_b32_e32 v253, 0
	v_lshl_add_u64 v[254:255], v[138:139], 0, v[252:253]
	global_load_dwordx4 v[238:241], v[254:255], off offset:1040
	global_load_dwordx4 v[242:245], v[254:255], off offset:1024
	v_lshl_add_u64 v[254:255], v[140:141], 0, v[252:253]
	global_load_dwordx4 v[248:251], v[254:255], off offset:1024
	global_load_dwordx4 v[252:255], v[254:255], off offset:1040
.LBB0_411:
	v_cvt_pk_bf16_f32 v130, v176, v177
	v_cvt_pk_bf16_f32 v131, v174, v175
	v_cvt_pk_bf16_f32 v132, v168, v169
	v_cvt_pk_bf16_f32 v133, v178, v179
	global_store_dwordx4 v[166:167], v[130:133], off offset:256
	v_pk_mul_f32 v[170:171], v[64:65], v[164:165] op_sel_hi:[1,0]
	v_pk_mul_f32 v[172:173], v[62:63], v[164:165] op_sel_hi:[1,0]
	v_lshlrev_b32_e32 v130, 6, v162
	v_and_b32_e32 v136, 0x1ffc0, v130
	v_lshl_add_u64 v[168:169], v[138:139], 0, v[136:137]
	v_lshl_add_u64 v[166:167], v[140:141], 0, v[136:137]
	v_pk_mul_f32 v[174:175], v[60:61], v[164:165] op_sel_hi:[1,0]
	s_and_b64 vcc, exec, s[6:7]
	v_pk_mul_f32 v[176:177], v[58:59], v[164:165] op_sel_hi:[1,0]
	s_cbranch_vccnz .LBB0_413
	v_mov_b32_e32 v136, v172
	v_mov_b32_e32 v147, v172
	s_nop 1
	v_permlane32_swap_b32_e32 v136, v147
	v_cndmask_b32_e64 v190, v136, v147, s[2:3]
	v_mov_b32_e32 v136, v176
	v_mov_b32_e32 v147, v176
	s_nop 1
	v_permlane32_swap_b32_e32 v136, v147
	v_cndmask_b32_e64 v192, v136, v147, s[2:3]
	v_mov_b32_e32 v136, v173
	v_mov_b32_e32 v147, v173
	s_nop 1
	v_permlane32_swap_b32_e32 v136, v147
	v_cndmask_b32_e64 v191, v136, v147, s[2:3]
	v_mov_b32_e32 v136, v177
	v_mov_b32_e32 v147, v177
	s_nop 1
	v_permlane32_swap_b32_e32 v136, v147
	v_cndmask_b32_e64 v193, v136, v147, s[2:3]
	v_mov_b32_e32 v136, v170
	v_mov_b32_e32 v147, v170
	s_nop 1
	v_permlane32_swap_b32_e32 v136, v147
	v_cndmask_b32_e64 v206, v136, v147, s[2:3]
	v_mov_b32_e32 v136, v174
	v_mov_b32_e32 v147, v174
	s_nop 1
	v_permlane32_swap_b32_e32 v136, v147
	v_cndmask_b32_e64 v210, v136, v147, s[2:3]
	v_mov_b32_e32 v136, v171
	v_mov_b32_e32 v147, v171
	s_nop 1
	v_permlane32_swap_b32_e32 v136, v147
	v_cndmask_b32_e64 v207, v136, v147, s[2:3]
	v_mov_b32_e32 v136, v175
	v_mov_b32_e32 v147, v175
	s_nop 1
	v_permlane32_swap_b32_e32 v136, v147
	v_cndmask_b32_e64 v211, v136, v147, s[2:3]
	s_waitcnt vmcnt(2)
	v_xor_b32_e32 v136, 0x80000000, v252
	v_xor_b32_e32 v147, 0x80000000, v253
	v_xor_b32_e32 v149, 0x80000000, v254
	v_xor_b32_e32 v151, 0x80000000, v255
	v_cndmask_b32_e64 v255, v255, v151, s[2:3]
	v_cndmask_b32_e64 v254, v254, v149, s[2:3]
	v_cndmask_b32_e64 v253, v253, v147, s[2:3]
	v_cndmask_b32_e64 v252, v252, v136, s[2:3]
	v_xor_b32_e32 v136, 0x80000000, v248
	v_xor_b32_e32 v147, 0x80000000, v249
	v_xor_b32_e32 v149, 0x80000000, v250
	v_xor_b32_e32 v151, 0x80000000, v251
	v_cndmask_b32_e64 v251, v251, v151, s[2:3]
	v_cndmask_b32_e64 v250, v250, v149, s[2:3]
	v_cndmask_b32_e64 v249, v249, v147, s[2:3]
	v_cndmask_b32_e64 v248, v248, v136, s[2:3]
	v_pk_mul_f32 v[248:249], v[248:249], v[190:191]
	v_pk_mul_f32 v[250:251], v[250:251], v[206:207]
	v_pk_fma_f32 v[172:173], v[172:173], v[242:243], v[248:249]
	v_pk_fma_f32 v[170:171], v[170:171], v[244:245], v[250:251]
	v_pk_mul_f32 v[242:243], v[252:253], v[192:193]
	v_pk_mul_f32 v[244:245], v[254:255], v[210:211]
	v_pk_fma_f32 v[176:177], v[176:177], v[238:239], v[242:243]
	v_pk_fma_f32 v[174:175], v[174:175], v[240:241], v[244:245]
	v_add_u32_e32 v252, 144, v144
	v_lshlrev_b32_e32 v252, 6, v252
	v_and_b32_e32 v252, 0x1ffc0, v252
	v_mov_b32_e32 v253, 0
	v_lshl_add_u64 v[254:255], v[138:139], 0, v[252:253]
	global_load_dwordx4 v[238:241], v[254:255], off offset:1040
	global_load_dwordx4 v[242:245], v[254:255], off offset:1024
	v_lshl_add_u64 v[254:255], v[140:141], 0, v[252:253]
	global_load_dwordx4 v[248:251], v[254:255], off offset:1024
	global_load_dwordx4 v[252:255], v[254:255], off offset:1040
.LBB0_413:
	v_mad_i64_i32 v[162:163], s[0:1], v162, s87, v[156:157]
	v_cvt_pk_bf16_f32 v130, v172, v173
	v_cvt_pk_bf16_f32 v131, v170, v171
	v_cvt_pk_bf16_f32 v132, v176, v177
	v_cvt_pk_bf16_f32 v133, v174, v175
	v_mov_b32_e32 v165, v164
	global_store_dwordx4 v[162:163], v[130:133], off
	v_pk_mul_f32 v[172:173], v[50:51], v[164:165]
	s_and_b64 vcc, exec, s[8:9]
	v_mov_b32_e32 v130, v164
	v_mov_b32_e32 v131, v164
	v_pk_mul_f32 v[170:171], v[52:53], v[130:131]
	v_pk_mul_f32 v[174:175], v[44:45], v[130:131]
	v_pk_mul_f32 v[164:165], v[42:43], v[164:165]
	s_cbranch_vccnz .LBB0_415
	v_mov_b32_e32 v136, v172
	v_mov_b32_e32 v147, v172
	s_nop 1
	v_permlane32_swap_b32_e32 v136, v147
	v_cndmask_b32_e64 v184, v136, v147, s[2:3]
	v_mov_b32_e32 v136, v164
	v_mov_b32_e32 v147, v164
	s_nop 1
	v_permlane32_swap_b32_e32 v136, v147
	v_cndmask_b32_e64 v186, v136, v147, s[2:3]
	v_mov_b32_e32 v136, v173
	v_mov_b32_e32 v147, v173
	s_nop 1
	v_permlane32_swap_b32_e32 v136, v147
	v_cndmask_b32_e64 v185, v136, v147, s[2:3]
	v_mov_b32_e32 v136, v165
	v_mov_b32_e32 v147, v165
	s_nop 1
	v_permlane32_swap_b32_e32 v136, v147
	v_cndmask_b32_e64 v187, v136, v147, s[2:3]
	v_mov_b32_e32 v136, v170
	v_mov_b32_e32 v147, v170
	s_nop 1
	v_permlane32_swap_b32_e32 v136, v147
	v_cndmask_b32_e64 v188, v136, v147, s[2:3]
	v_mov_b32_e32 v136, v174
	v_mov_b32_e32 v147, v174
	s_nop 1
	v_permlane32_swap_b32_e32 v136, v147
	v_cndmask_b32_e64 v190, v136, v147, s[2:3]
	v_mov_b32_e32 v136, v171
	v_mov_b32_e32 v147, v171
	s_nop 1
	v_permlane32_swap_b32_e32 v136, v147
	v_cndmask_b32_e64 v189, v136, v147, s[2:3]
	v_mov_b32_e32 v136, v175
	v_mov_b32_e32 v147, v175
	s_nop 1
	v_permlane32_swap_b32_e32 v136, v147
	v_cndmask_b32_e64 v191, v136, v147, s[2:3]
	s_waitcnt vmcnt(2)
	v_xor_b32_e32 v136, 0x80000000, v252
	v_xor_b32_e32 v147, 0x80000000, v253
	v_xor_b32_e32 v149, 0x80000000, v254
	v_xor_b32_e32 v151, 0x80000000, v255
	v_cndmask_b32_e64 v255, v255, v151, s[2:3]
	v_cndmask_b32_e64 v254, v254, v149, s[2:3]
	v_cndmask_b32_e64 v253, v253, v147, s[2:3]
	v_cndmask_b32_e64 v252, v252, v136, s[2:3]
	v_xor_b32_e32 v136, 0x80000000, v248
	v_xor_b32_e32 v147, 0x80000000, v249
	v_xor_b32_e32 v149, 0x80000000, v250
	v_xor_b32_e32 v151, 0x80000000, v251
	v_cndmask_b32_e64 v251, v251, v151, s[2:3]
	v_cndmask_b32_e64 v250, v250, v149, s[2:3]
	v_cndmask_b32_e64 v249, v249, v147, s[2:3]
	v_cndmask_b32_e64 v248, v248, v136, s[2:3]
	v_pk_mul_f32 v[248:249], v[248:249], v[184:185]
	v_pk_mul_f32 v[250:251], v[250:251], v[188:189]
	v_pk_mul_f32 v[252:253], v[252:253], v[186:187]
	v_pk_mul_f32 v[254:255], v[254:255], v[190:191]
	v_pk_fma_f32 v[170:171], v[170:171], v[244:245], v[250:251]
	v_pk_fma_f32 v[172:173], v[172:173], v[242:243], v[248:249]
	v_pk_fma_f32 v[174:175], v[174:175], v[240:241], v[254:255]
	v_pk_fma_f32 v[164:165], v[164:165], v[238:239], v[252:253]
	v_add_u32_e32 v252, 144, v144
	v_lshlrev_b32_e32 v252, 6, v252
	v_and_b32_e32 v252, 0x1ffc0, v252
	v_mov_b32_e32 v253, 0
	v_lshl_add_u64 v[254:255], v[138:139], 0, v[252:253]
	global_load_dwordx4 v[238:241], v[254:255], off offset:1040
	global_load_dwordx4 v[242:245], v[254:255], off offset:1024
	v_lshl_add_u64 v[254:255], v[140:141], 0, v[252:253]
	global_load_dwordx4 v[248:251], v[254:255], off offset:1024
	global_load_dwordx4 v[252:255], v[254:255], off offset:1040
.LBB0_415:
	v_cvt_pk_bf16_f32 v130, v172, v173
	v_cvt_pk_bf16_f32 v131, v170, v171
	v_cvt_pk_bf16_f32 v132, v164, v165
	v_cvt_pk_bf16_f32 v133, v174, v175
	global_store_dwordx4 v[162:163], v[130:133], off offset:256
	v_pk_mul_f32 v[166:167], v[56:57], v[160:161] op_sel_hi:[1,0]
	v_pk_mul_f32 v[168:169], v[54:55], v[160:161] op_sel_hi:[1,0]
	v_lshlrev_b32_e32 v130, 6, v158
	v_and_b32_e32 v136, 0x1ffc0, v130
	v_lshl_add_u64 v[164:165], v[138:139], 0, v[136:137]
	v_lshl_add_u64 v[162:163], v[140:141], 0, v[136:137]
	v_pk_mul_f32 v[170:171], v[48:49], v[160:161] op_sel_hi:[1,0]
	s_and_b64 vcc, exec, s[6:7]
	v_pk_mul_f32 v[172:173], v[46:47], v[160:161] op_sel_hi:[1,0]
	s_cbranch_vccnz .LBB0_417
	v_mov_b32_e32 v136, v168
	v_mov_b32_e32 v147, v168
	s_nop 1
	v_permlane32_swap_b32_e32 v136, v147
	v_cndmask_b32_e64 v186, v136, v147, s[2:3]
	v_mov_b32_e32 v136, v172
	v_mov_b32_e32 v147, v172
	s_nop 1
	v_permlane32_swap_b32_e32 v136, v147
	v_cndmask_b32_e64 v188, v136, v147, s[2:3]
	v_mov_b32_e32 v136, v169
	v_mov_b32_e32 v147, v169
	s_nop 1
	v_permlane32_swap_b32_e32 v136, v147
	v_cndmask_b32_e64 v187, v136, v147, s[2:3]
	v_mov_b32_e32 v136, v173
	v_mov_b32_e32 v147, v173
	s_nop 1
	v_permlane32_swap_b32_e32 v136, v147
	v_cndmask_b32_e64 v189, v136, v147, s[2:3]
	v_mov_b32_e32 v136, v166
	v_mov_b32_e32 v147, v166
	s_nop 1
	v_permlane32_swap_b32_e32 v136, v147
	v_cndmask_b32_e64 v190, v136, v147, s[2:3]
	v_mov_b32_e32 v136, v170
	v_mov_b32_e32 v147, v170
	s_nop 1
	v_permlane32_swap_b32_e32 v136, v147
	v_cndmask_b32_e64 v192, v136, v147, s[2:3]
	v_mov_b32_e32 v136, v167
	v_mov_b32_e32 v147, v167
	s_nop 1
	v_permlane32_swap_b32_e32 v136, v147
	v_cndmask_b32_e64 v191, v136, v147, s[2:3]
	v_mov_b32_e32 v136, v171
	v_mov_b32_e32 v147, v171
	s_nop 1
	v_permlane32_swap_b32_e32 v136, v147
	v_cndmask_b32_e64 v193, v136, v147, s[2:3]
	s_waitcnt vmcnt(2)
	v_xor_b32_e32 v136, 0x80000000, v252
	v_xor_b32_e32 v147, 0x80000000, v253
	v_xor_b32_e32 v149, 0x80000000, v254
	v_xor_b32_e32 v151, 0x80000000, v255
	v_cndmask_b32_e64 v255, v255, v151, s[2:3]
	v_cndmask_b32_e64 v254, v254, v149, s[2:3]
	v_cndmask_b32_e64 v253, v253, v147, s[2:3]
	v_cndmask_b32_e64 v252, v252, v136, s[2:3]
	v_xor_b32_e32 v136, 0x80000000, v248
	v_xor_b32_e32 v147, 0x80000000, v249
	v_xor_b32_e32 v149, 0x80000000, v250
	v_xor_b32_e32 v151, 0x80000000, v251
	v_cndmask_b32_e64 v251, v251, v151, s[2:3]
	v_cndmask_b32_e64 v250, v250, v149, s[2:3]
	v_cndmask_b32_e64 v249, v249, v147, s[2:3]
	v_cndmask_b32_e64 v248, v248, v136, s[2:3]
	v_pk_mul_f32 v[248:249], v[248:249], v[186:187]
	v_pk_mul_f32 v[250:251], v[250:251], v[190:191]
	v_pk_fma_f32 v[168:169], v[168:169], v[242:243], v[248:249]
	v_pk_fma_f32 v[166:167], v[166:167], v[244:245], v[250:251]
	v_pk_mul_f32 v[242:243], v[252:253], v[188:189]
	v_pk_mul_f32 v[244:245], v[254:255], v[192:193]
	v_pk_fma_f32 v[172:173], v[172:173], v[238:239], v[242:243]
	v_pk_fma_f32 v[170:171], v[170:171], v[240:241], v[244:245]
	v_add_u32_e32 v252, 160, v144
	v_lshlrev_b32_e32 v252, 6, v252
	v_and_b32_e32 v252, 0x1ffc0, v252
	v_mov_b32_e32 v253, 0
	v_lshl_add_u64 v[254:255], v[138:139], 0, v[252:253]
	global_load_dwordx4 v[238:241], v[254:255], off offset:1040
	global_load_dwordx4 v[242:245], v[254:255], off offset:1024
	v_lshl_add_u64 v[254:255], v[140:141], 0, v[252:253]
	global_load_dwordx4 v[248:251], v[254:255], off offset:1024
	global_load_dwordx4 v[252:255], v[254:255], off offset:1040
.LBB0_417:
	v_mad_i64_i32 v[158:159], s[0:1], v158, s87, v[156:157]
	v_cvt_pk_bf16_f32 v130, v168, v169
	v_cvt_pk_bf16_f32 v131, v166, v167
	v_cvt_pk_bf16_f32 v132, v172, v173
	v_cvt_pk_bf16_f32 v133, v170, v171
	v_mov_b32_e32 v161, v160
	global_store_dwordx4 v[158:159], v[130:133], off
	v_pk_mul_f32 v[168:169], v[34:35], v[160:161]
	s_and_b64 vcc, exec, s[8:9]
	v_mov_b32_e32 v130, v160
	v_mov_b32_e32 v131, v160
	v_pk_mul_f32 v[166:167], v[36:37], v[130:131]
	v_pk_mul_f32 v[170:171], v[28:29], v[130:131]
	v_pk_mul_f32 v[160:161], v[26:27], v[160:161]
	s_cbranch_vccnz .LBB0_419
	v_mov_b32_e32 v136, v168
	v_mov_b32_e32 v147, v168
	s_nop 1
	v_permlane32_swap_b32_e32 v136, v147
	v_cndmask_b32_e64 v180, v136, v147, s[2:3]
	v_mov_b32_e32 v136, v160
	v_mov_b32_e32 v147, v160
	s_nop 1
	v_permlane32_swap_b32_e32 v136, v147
	v_cndmask_b32_e64 v182, v136, v147, s[2:3]
	v_mov_b32_e32 v136, v169
	v_mov_b32_e32 v147, v169
	s_nop 1
	v_permlane32_swap_b32_e32 v136, v147
	v_cndmask_b32_e64 v181, v136, v147, s[2:3]
	v_mov_b32_e32 v136, v161
	v_mov_b32_e32 v147, v161
	s_nop 1
	v_permlane32_swap_b32_e32 v136, v147
	v_cndmask_b32_e64 v183, v136, v147, s[2:3]
	v_mov_b32_e32 v136, v166
	v_mov_b32_e32 v147, v166
	s_nop 1
	v_permlane32_swap_b32_e32 v136, v147
	v_cndmask_b32_e64 v184, v136, v147, s[2:3]
	v_mov_b32_e32 v136, v170
	v_mov_b32_e32 v147, v170
	s_nop 1
	v_permlane32_swap_b32_e32 v136, v147
	v_cndmask_b32_e64 v186, v136, v147, s[2:3]
	v_mov_b32_e32 v136, v167
	v_mov_b32_e32 v147, v167
	s_nop 1
	v_permlane32_swap_b32_e32 v136, v147
	v_cndmask_b32_e64 v185, v136, v147, s[2:3]
	v_mov_b32_e32 v136, v171
	v_mov_b32_e32 v147, v171
	s_nop 1
	v_permlane32_swap_b32_e32 v136, v147
	v_cndmask_b32_e64 v187, v136, v147, s[2:3]
	s_waitcnt vmcnt(2)
	v_xor_b32_e32 v136, 0x80000000, v252
	v_xor_b32_e32 v147, 0x80000000, v253
	v_xor_b32_e32 v149, 0x80000000, v254
	v_xor_b32_e32 v151, 0x80000000, v255
	v_cndmask_b32_e64 v255, v255, v151, s[2:3]
	v_cndmask_b32_e64 v254, v254, v149, s[2:3]
	v_cndmask_b32_e64 v253, v253, v147, s[2:3]
	v_cndmask_b32_e64 v252, v252, v136, s[2:3]
	v_xor_b32_e32 v136, 0x80000000, v248
	v_xor_b32_e32 v147, 0x80000000, v249
	v_xor_b32_e32 v149, 0x80000000, v250
	v_xor_b32_e32 v151, 0x80000000, v251
	v_cndmask_b32_e64 v251, v251, v151, s[2:3]
	v_cndmask_b32_e64 v250, v250, v149, s[2:3]
	v_cndmask_b32_e64 v249, v249, v147, s[2:3]
	v_cndmask_b32_e64 v248, v248, v136, s[2:3]
	v_pk_mul_f32 v[248:249], v[248:249], v[180:181]
	v_pk_mul_f32 v[250:251], v[250:251], v[184:185]
	v_pk_mul_f32 v[252:253], v[252:253], v[182:183]
	v_pk_mul_f32 v[254:255], v[254:255], v[186:187]
	v_pk_fma_f32 v[166:167], v[166:167], v[244:245], v[250:251]
	v_pk_fma_f32 v[168:169], v[168:169], v[242:243], v[248:249]
	v_pk_fma_f32 v[170:171], v[170:171], v[240:241], v[254:255]
	v_pk_fma_f32 v[160:161], v[160:161], v[238:239], v[252:253]
	v_add_u32_e32 v252, 160, v144
	v_lshlrev_b32_e32 v252, 6, v252
	v_and_b32_e32 v252, 0x1ffc0, v252
	v_mov_b32_e32 v253, 0
	v_lshl_add_u64 v[254:255], v[138:139], 0, v[252:253]
	global_load_dwordx4 v[238:241], v[254:255], off offset:1040
	global_load_dwordx4 v[242:245], v[254:255], off offset:1024
	v_lshl_add_u64 v[254:255], v[140:141], 0, v[252:253]
	global_load_dwordx4 v[248:251], v[254:255], off offset:1024
	global_load_dwordx4 v[252:255], v[254:255], off offset:1040
.LBB0_419:
	v_cvt_pk_bf16_f32 v130, v168, v169
	v_cvt_pk_bf16_f32 v131, v166, v167
	v_cvt_pk_bf16_f32 v132, v160, v161
	v_cvt_pk_bf16_f32 v133, v170, v171
	global_store_dwordx4 v[158:159], v[130:133], off offset:256
	v_pk_mul_f32 v[162:163], v[40:41], v[154:155] op_sel_hi:[1,0]
	v_pk_mul_f32 v[164:165], v[38:39], v[154:155] op_sel_hi:[1,0]
	v_lshlrev_b32_e32 v130, 6, v152
	v_and_b32_e32 v136, 0x1ffc0, v130
	v_lshl_add_u64 v[160:161], v[138:139], 0, v[136:137]
	v_lshl_add_u64 v[158:159], v[140:141], 0, v[136:137]
	v_pk_mul_f32 v[166:167], v[32:33], v[154:155] op_sel_hi:[1,0]
	s_and_b64 vcc, exec, s[6:7]
	v_pk_mul_f32 v[168:169], v[30:31], v[154:155] op_sel_hi:[1,0]
	s_cbranch_vccnz .LBB0_421
	v_mov_b32_e32 v136, v164
	v_mov_b32_e32 v147, v164
	s_nop 1
	v_permlane32_swap_b32_e32 v136, v147
	v_cndmask_b32_e64 v182, v136, v147, s[2:3]
	v_mov_b32_e32 v136, v168
	v_mov_b32_e32 v147, v168
	s_nop 1
	v_permlane32_swap_b32_e32 v136, v147
	v_cndmask_b32_e64 v184, v136, v147, s[2:3]
	v_mov_b32_e32 v136, v165
	v_mov_b32_e32 v147, v165
	s_nop 1
	v_permlane32_swap_b32_e32 v136, v147
	v_cndmask_b32_e64 v183, v136, v147, s[2:3]
	v_mov_b32_e32 v136, v169
	v_mov_b32_e32 v147, v169
	s_nop 1
	v_permlane32_swap_b32_e32 v136, v147
	v_cndmask_b32_e64 v185, v136, v147, s[2:3]
	v_mov_b32_e32 v136, v162
	v_mov_b32_e32 v147, v162
	s_nop 1
	v_permlane32_swap_b32_e32 v136, v147
	v_cndmask_b32_e64 v186, v136, v147, s[2:3]
	v_mov_b32_e32 v136, v166
	v_mov_b32_e32 v147, v166
	s_nop 1
	v_permlane32_swap_b32_e32 v136, v147
	v_cndmask_b32_e64 v188, v136, v147, s[2:3]
	v_mov_b32_e32 v136, v163
	v_mov_b32_e32 v147, v163
	s_nop 1
	v_permlane32_swap_b32_e32 v136, v147
	v_cndmask_b32_e64 v187, v136, v147, s[2:3]
	v_mov_b32_e32 v136, v167
	v_mov_b32_e32 v147, v167
	s_nop 1
	v_permlane32_swap_b32_e32 v136, v147
	v_cndmask_b32_e64 v189, v136, v147, s[2:3]
	s_waitcnt vmcnt(2)
	v_xor_b32_e32 v136, 0x80000000, v252
	v_xor_b32_e32 v147, 0x80000000, v253
	v_xor_b32_e32 v149, 0x80000000, v254
	v_xor_b32_e32 v151, 0x80000000, v255
	v_cndmask_b32_e64 v255, v255, v151, s[2:3]
	v_cndmask_b32_e64 v254, v254, v149, s[2:3]
	v_cndmask_b32_e64 v253, v253, v147, s[2:3]
	v_cndmask_b32_e64 v252, v252, v136, s[2:3]
	v_xor_b32_e32 v136, 0x80000000, v248
	v_xor_b32_e32 v147, 0x80000000, v249
	v_xor_b32_e32 v149, 0x80000000, v250
	v_xor_b32_e32 v151, 0x80000000, v251
	v_cndmask_b32_e64 v251, v251, v151, s[2:3]
	v_cndmask_b32_e64 v250, v250, v149, s[2:3]
	v_cndmask_b32_e64 v249, v249, v147, s[2:3]
	v_cndmask_b32_e64 v248, v248, v136, s[2:3]
	v_pk_mul_f32 v[248:249], v[248:249], v[182:183]
	v_pk_mul_f32 v[250:251], v[250:251], v[186:187]
	v_pk_fma_f32 v[164:165], v[164:165], v[242:243], v[248:249]
	v_pk_fma_f32 v[162:163], v[162:163], v[244:245], v[250:251]
	v_pk_mul_f32 v[242:243], v[252:253], v[184:185]
	v_pk_mul_f32 v[244:245], v[254:255], v[188:189]
	v_pk_fma_f32 v[168:169], v[168:169], v[238:239], v[242:243]
	v_pk_fma_f32 v[166:167], v[166:167], v[240:241], v[244:245]
	v_add_u32_e32 v252, 176, v144
	v_lshlrev_b32_e32 v252, 6, v252
	v_and_b32_e32 v252, 0x1ffc0, v252
	v_mov_b32_e32 v253, 0
	v_lshl_add_u64 v[254:255], v[140:141], 0, v[252:253]
	global_load_dwordx4 v[238:241], v[254:255], off offset:1040
	global_load_dwordx4 v[242:245], v[254:255], off offset:1024
	v_lshl_add_u64 v[254:255], v[138:139], 0, v[252:253]
	global_load_dwordx4 v[248:251], v[254:255], off offset:1024
	global_load_dwordx4 v[252:255], v[254:255], off offset:1040
.LBB0_421:
	v_mad_i64_i32 v[152:153], s[0:1], v152, s87, v[156:157]
	v_cvt_pk_bf16_f32 v130, v164, v165
	v_cvt_pk_bf16_f32 v131, v162, v163
	v_cvt_pk_bf16_f32 v132, v168, v169
	v_cvt_pk_bf16_f32 v133, v166, v167
	v_mov_b32_e32 v155, v154
	global_store_dwordx4 v[152:153], v[130:133], off
	v_pk_mul_f32 v[164:165], v[18:19], v[154:155]
	s_and_b64 vcc, exec, s[8:9]
	v_mov_b32_e32 v130, v154
	v_mov_b32_e32 v131, v154
	v_pk_mul_f32 v[162:163], v[20:21], v[130:131]
	v_pk_mul_f32 v[166:167], v[12:13], v[130:131]
	v_pk_mul_f32 v[154:155], v[10:11], v[154:155]
	s_cbranch_vccnz .LBB0_423
	v_mov_b32_e32 v136, v164
	v_mov_b32_e32 v147, v164
	s_nop 1
	v_permlane32_swap_b32_e32 v136, v147
	v_cndmask_b32_e64 v176, v136, v147, s[2:3]
	v_mov_b32_e32 v136, v154
	v_mov_b32_e32 v147, v154
	s_nop 1
	v_permlane32_swap_b32_e32 v136, v147
	v_cndmask_b32_e64 v178, v136, v147, s[2:3]
	v_mov_b32_e32 v136, v165
	v_mov_b32_e32 v147, v165
	s_nop 1
	v_permlane32_swap_b32_e32 v136, v147
	v_cndmask_b32_e64 v177, v136, v147, s[2:3]
	v_mov_b32_e32 v136, v155
	v_mov_b32_e32 v147, v155
	s_nop 1
	v_permlane32_swap_b32_e32 v136, v147
	v_cndmask_b32_e64 v179, v136, v147, s[2:3]
	v_mov_b32_e32 v136, v162
	v_mov_b32_e32 v147, v162
	s_nop 1
	v_permlane32_swap_b32_e32 v136, v147
	v_cndmask_b32_e64 v180, v136, v147, s[2:3]
	v_mov_b32_e32 v136, v166
	v_mov_b32_e32 v147, v166
	s_nop 1
	v_permlane32_swap_b32_e32 v136, v147
	v_cndmask_b32_e64 v182, v136, v147, s[2:3]
	v_mov_b32_e32 v136, v163
	v_mov_b32_e32 v147, v163
	s_nop 1
	v_permlane32_swap_b32_e32 v136, v147
	v_cndmask_b32_e64 v181, v136, v147, s[2:3]
	v_mov_b32_e32 v136, v167
	v_mov_b32_e32 v147, v167
	s_nop 1
	v_permlane32_swap_b32_e32 v136, v147
	v_cndmask_b32_e64 v183, v136, v147, s[2:3]
	s_waitcnt vmcnt(2)
	v_xor_b32_e32 v136, 0x80000000, v252
	v_xor_b32_e32 v147, 0x80000000, v253
	v_xor_b32_e32 v149, 0x80000000, v254
	v_xor_b32_e32 v151, 0x80000000, v255
	v_cndmask_b32_e64 v255, v255, v151, s[2:3]
	v_cndmask_b32_e64 v254, v254, v149, s[2:3]
	v_cndmask_b32_e64 v253, v253, v147, s[2:3]
	v_cndmask_b32_e64 v252, v252, v136, s[2:3]
	v_xor_b32_e32 v136, 0x80000000, v248
	v_xor_b32_e32 v147, 0x80000000, v249
	v_xor_b32_e32 v149, 0x80000000, v250
	v_xor_b32_e32 v151, 0x80000000, v251
	v_cndmask_b32_e64 v251, v251, v151, s[2:3]
	v_cndmask_b32_e64 v250, v250, v149, s[2:3]
	v_cndmask_b32_e64 v249, v249, v147, s[2:3]
	v_cndmask_b32_e64 v248, v248, v136, s[2:3]
	v_pk_mul_f32 v[248:249], v[248:249], v[176:177]
	v_pk_mul_f32 v[250:251], v[250:251], v[180:181]
	v_pk_mul_f32 v[252:253], v[252:253], v[178:179]
	v_pk_mul_f32 v[254:255], v[254:255], v[182:183]
	v_pk_fma_f32 v[162:163], v[162:163], v[244:245], v[250:251]
	v_pk_fma_f32 v[164:165], v[164:165], v[242:243], v[248:249]
	v_pk_fma_f32 v[166:167], v[166:167], v[240:241], v[254:255]
	v_pk_fma_f32 v[154:155], v[154:155], v[238:239], v[252:253]
	v_add_u32_e32 v252, 176, v144
	v_lshlrev_b32_e32 v252, 6, v252
	v_and_b32_e32 v252, 0x1ffc0, v252
	v_mov_b32_e32 v253, 0
	v_lshl_add_u64 v[254:255], v[140:141], 0, v[252:253]
	global_load_dwordx4 v[238:241], v[254:255], off offset:1040
	global_load_dwordx4 v[242:245], v[254:255], off offset:1024
	v_lshl_add_u64 v[254:255], v[138:139], 0, v[252:253]
	global_load_dwordx4 v[248:251], v[254:255], off offset:1024
	global_load_dwordx4 v[252:255], v[254:255], off offset:1040
.LBB0_423:
	v_cvt_pk_bf16_f32 v130, v164, v165
	v_cvt_pk_bf16_f32 v131, v162, v163
	v_cvt_pk_bf16_f32 v132, v154, v155
	v_cvt_pk_bf16_f32 v133, v166, v167
	global_store_dwordx4 v[152:153], v[130:133], off offset:256
	v_pk_mul_f32 v[152:153], v[24:25], v[150:151] op_sel_hi:[1,0]
	v_pk_mul_f32 v[154:155], v[22:23], v[150:151] op_sel_hi:[1,0]
	v_lshlrev_b32_e32 v130, 6, v148
	v_and_b32_e32 v136, 0x1ffc0, v130
	v_lshl_add_u64 v[130:131], v[138:139], 0, v[136:137]
	v_lshl_add_u64 v[132:133], v[140:141], 0, v[136:137]
	v_pk_mul_f32 v[158:159], v[16:17], v[150:151] op_sel_hi:[1,0]
	s_and_b64 vcc, exec, s[6:7]
	v_pk_mul_f32 v[160:161], v[14:15], v[150:151] op_sel_hi:[1,0]
	s_cbranch_vccnz .LBB0_425
	v_mov_b32_e32 v136, v154
	v_mov_b32_e32 v147, v154
	v_mov_b32_e32 v149, v160
	v_mov_b32_e32 v151, v160
	v_mov_b32_e32 v179, v155
	v_mov_b32_e32 v181, v155
	v_mov_b32_e32 v182, v161
	v_mov_b32_e32 v183, v161
	v_mov_b32_e32 v184, v152
	v_mov_b32_e32 v185, v152
	v_mov_b32_e32 v186, v158
	v_mov_b32_e32 v187, v158
	v_mov_b32_e32 v188, v153
	v_mov_b32_e32 v189, v153
	v_mov_b32_e32 v190, v159
	v_mov_b32_e32 v191, v159
	v_permlane32_swap_b32_e32 v136, v147
	v_permlane32_swap_b32_e32 v149, v151
	v_permlane32_swap_b32_e32 v179, v181
	v_permlane32_swap_b32_e32 v182, v183
	v_permlane32_swap_b32_e32 v184, v185
	v_permlane32_swap_b32_e32 v186, v187
	v_permlane32_swap_b32_e32 v188, v189
	v_permlane32_swap_b32_e32 v190, v191
	v_cndmask_b32_e64 v178, v136, v147, s[2:3]
	v_cndmask_b32_e64 v180, v149, v151, s[2:3]
	v_cndmask_b32_e64 v179, v179, v181, s[2:3]
	v_cndmask_b32_e64 v181, v182, v183, s[2:3]
	v_cndmask_b32_e64 v182, v184, v185, s[2:3]
	v_cndmask_b32_e64 v184, v186, v187, s[2:3]
	v_cndmask_b32_e64 v183, v188, v189, s[2:3]
	v_cndmask_b32_e64 v185, v190, v191, s[2:3]
	s_waitcnt vmcnt(2)
	v_xor_b32_e32 v136, 0x80000000, v238
	v_xor_b32_e32 v147, 0x80000000, v239
	v_xor_b32_e32 v149, 0x80000000, v240
	v_xor_b32_e32 v151, 0x80000000, v241
	v_xor_b32_e32 v186, 0x80000000, v242
	v_xor_b32_e32 v187, 0x80000000, v243
	v_xor_b32_e32 v188, 0x80000000, v244
	v_xor_b32_e32 v189, 0x80000000, v245
	v_cndmask_b32_e64 v241, v241, v151, s[2:3]
	v_cndmask_b32_e64 v240, v240, v149, s[2:3]
	v_cndmask_b32_e64 v239, v239, v147, s[2:3]
	v_cndmask_b32_e64 v238, v238, v136, s[2:3]
	v_cndmask_b32_e64 v245, v245, v189, s[2:3]
	v_cndmask_b32_e64 v244, v244, v188, s[2:3]
	v_cndmask_b32_e64 v243, v243, v187, s[2:3]
	v_cndmask_b32_e64 v242, v242, v186, s[2:3]
	v_pk_mul_f32 v[242:243], v[242:243], v[178:179]
	v_pk_mul_f32 v[244:245], v[244:245], v[182:183]
	v_pk_mul_f32 v[238:239], v[238:239], v[180:181]
	v_pk_mul_f32 v[240:241], v[240:241], v[184:185]
	v_pk_fma_f32 v[152:153], v[152:153], v[250:251], v[244:245]
	v_pk_fma_f32 v[154:155], v[154:155], v[248:249], v[242:243]
	v_pk_fma_f32 v[158:159], v[158:159], v[254:255], v[240:241]
	v_pk_fma_f32 v[160:161], v[160:161], v[252:253], v[238:239]
.LBB0_425:
	v_mad_i64_i32 v[148:149], s[0:1], v148, s87, v[156:157]
	v_cvt_pk_bf16_f32 v154, v154, v155
	v_cvt_pk_bf16_f32 v155, v152, v153
	v_cvt_pk_bf16_f32 v156, v160, v161
	v_cvt_pk_bf16_f32 v157, v158, v159
	v_mov_b32_e32 v151, v150
	global_store_dwordx4 v[148:149], v[154:157], off
	s_and_b64 vcc, exec, s[8:9]
	s_nop 0
	v_mov_b32_e32 v156, v150
	v_mov_b32_e32 v157, v150
	v_pk_mul_f32 v[152:153], v[8:9], v[156:157]
	v_pk_mul_f32 v[154:155], v[6:7], v[150:151]
	v_pk_mul_f32 v[156:157], v[4:5], v[156:157]
	v_pk_mul_f32 v[150:151], v[2:3], v[150:151]
	s_cbranch_vccnz .LBB0_427
	v_mov_b32_e32 v136, v154
	v_mov_b32_e32 v147, v154
	v_mov_b32_e32 v171, v150
	v_mov_b32_e32 v172, v150
	v_mov_b32_e32 v173, v155
	v_mov_b32_e32 v174, v155
	v_mov_b32_e32 v175, v151
	v_mov_b32_e32 v176, v151
	v_mov_b32_e32 v177, v152
	v_mov_b32_e32 v178, v152
	v_mov_b32_e32 v179, v156
	v_mov_b32_e32 v180, v156
	v_mov_b32_e32 v181, v153
	v_mov_b32_e32 v182, v153
	v_mov_b32_e32 v183, v157
	v_mov_b32_e32 v184, v157
	v_permlane32_swap_b32_e32 v136, v147
	v_permlane32_swap_b32_e32 v171, v172
	v_permlane32_swap_b32_e32 v173, v174
	v_permlane32_swap_b32_e32 v175, v176
	v_permlane32_swap_b32_e32 v177, v178
	v_permlane32_swap_b32_e32 v179, v180
	v_permlane32_swap_b32_e32 v181, v182
	v_permlane32_swap_b32_e32 v183, v184
	v_cndmask_b32_e64 v170, v136, v147, s[2:3]
	v_cndmask_b32_e64 v172, v171, v172, s[2:3]
	v_cndmask_b32_e64 v171, v173, v174, s[2:3]
	v_cndmask_b32_e64 v173, v175, v176, s[2:3]
	v_cndmask_b32_e64 v174, v177, v178, s[2:3]
	v_cndmask_b32_e64 v176, v179, v180, s[2:3]
	v_cndmask_b32_e64 v175, v181, v182, s[2:3]
	v_cndmask_b32_e64 v177, v183, v184, s[2:3]
	s_waitcnt vmcnt(2)
	v_xor_b32_e32 v136, 0x80000000, v238
	v_xor_b32_e32 v147, 0x80000000, v239
	v_xor_b32_e32 v178, 0x80000000, v240
	v_xor_b32_e32 v179, 0x80000000, v241
	v_xor_b32_e32 v180, 0x80000000, v242
	v_xor_b32_e32 v181, 0x80000000, v243
	v_xor_b32_e32 v182, 0x80000000, v244
	v_xor_b32_e32 v183, 0x80000000, v245
	v_cndmask_b32_e64 v241, v241, v179, s[2:3]
	v_cndmask_b32_e64 v240, v240, v178, s[2:3]
	v_cndmask_b32_e64 v239, v239, v147, s[2:3]
	v_cndmask_b32_e64 v238, v238, v136, s[2:3]
	v_cndmask_b32_e64 v245, v245, v183, s[2:3]
	v_cndmask_b32_e64 v244, v244, v182, s[2:3]
	v_cndmask_b32_e64 v243, v243, v181, s[2:3]
	v_cndmask_b32_e64 v242, v242, v180, s[2:3]
	v_pk_mul_f32 v[242:243], v[242:243], v[170:171]
	v_pk_mul_f32 v[244:245], v[244:245], v[174:175]
	v_pk_mul_f32 v[238:239], v[238:239], v[172:173]
	v_pk_mul_f32 v[240:241], v[240:241], v[176:177]
	v_pk_fma_f32 v[152:153], v[152:153], v[250:251], v[244:245]
	v_pk_fma_f32 v[154:155], v[154:155], v[248:249], v[242:243]
	v_pk_fma_f32 v[156:157], v[156:157], v[254:255], v[240:241]
	v_pk_fma_f32 v[150:151], v[150:151], v[252:253], v[238:239]
